# grid barrier: hand-written tail after the arrival atomic - the XCD's last arriver writes back and bumps the top-level counter without waiting for its value, every workgroup polls that counter for (gen
# speedup vs baseline: 1.0469x; 1.0047x over previous
.LBB0_134:
	s_or_b64 exec, exec, s[6:7]
	s_waitcnt vmcnt(0) lgkmcnt(0)
	v_readfirstlane_b32 s4, v4
	v_readfirstlane_b32 s5, v3
	v_readfirstlane_b32 s6, v1
	s_nop 0
	s_mov_b32 s7, 0
	s_mov_b32 s8, s5
	s_cmp_ge_u32 s4, s8
	s_addc_u32 s7, s7, 0
	s_add_u32 s8, s8, s5
	s_cmp_ge_u32 s4, s8
	s_addc_u32 s7, s7, 0
	s_add_u32 s8, s8, s5
	s_cmp_ge_u32 s4, s8
	s_addc_u32 s7, s7, 0
	s_add_u32 s8, s8, s5
	s_cmp_ge_u32 s4, s8
	s_addc_u32 s7, s7, 0
	s_add_u32 s8, s8, s5
	s_cmp_ge_u32 s4, s8
	s_addc_u32 s7, s7, 0
	s_add_u32 s8, s8, s5
	s_cmp_ge_u32 s4, s8
	s_addc_u32 s7, s7, 0
	s_add_u32 s8, s8, s5
	s_cmp_ge_u32 s4, s8
	s_addc_u32 s7, s7, 0
	s_add_u32 s8, s8, s5
	s_cmp_ge_u32 s4, s8
	s_addc_u32 s7, s7, 0
	s_add_u32 s8, s8, s5
	s_cmp_ge_u32 s4, s8
	s_addc_u32 s7, s7, 0
	s_add_u32 s8, s8, s5
	s_cmp_ge_u32 s4, s8
	s_addc_u32 s7, s7, 0
	s_add_u32 s8, s8, s5
	s_add_i32 s9, s7, 1
	s_mul_i32 s10, s9, s5
	s_mul_i32 s12, s9, s6
	s_add_u32 s2, s20, 0x1a02dc00
	s_addc_u32 s3, s21, 0
	v_mov_b32_e32 v1, 0
	s_add_i32 s11, s4, 1
	s_cmp_eq_u32 s11, s10
	s_cbranch_scc0 .Lgb1_poll
	buffer_wbl2 sc1
	s_waitcnt vmcnt(0)
	v_mov_b32_e32 v2, 1
	global_atomic_add v1, v2, s[2:3]
.Lgb1_poll:
	global_load_dword v3, v1, s[2:3] sc1
	s_waitcnt vmcnt(0)
	v_readfirstlane_b32 s13, v3
	s_nop 0
	s_cmp_ge_u32 s13, s12
	s_cbranch_scc1 .Lgb1_done
	s_sleep 1
	s_branch .Lgb1_poll
.Lgb1_done:
.LBB0_168:
	s_or_b64 exec, exec, s[0:1]
	s_mov_b64 s[0:1], 0
	s_waitcnt lgkmcnt(0)
	s_barrier

.Lgb9_done:
.LBB0_1449:
	s_or_b64 exec, exec, s[0:1]
	s_waitcnt lgkmcnt(0)
	s_barrier
